# code placement: MLA, FOX and merge-GEMM loop heads aligned to 64 bytes
# speedup vs baseline: 1.0040x; 1.0040x over previous
;     ...
;     float qn = 0.f;
;     if (MODE == 0 && DESC) {
; #pragma unroll
;         for (int s = 0; s < NKS; ++s)
; #pragma unroll
;             for (int j = 0; j < 8; ++j) { const float a = __uint_as_float(((unsigned)(unsigned short)qf[s][j]) << 16); qn += a * a; }
;         qn += xhalf_other(qn, h);
;         qn = sqrtf(qn) * kmax;
;     }
;     f32x16 o0, o1;
; #pragma unroll
;     for (int i = 0; i < 16; ++i) { o0[i] = 0.f; o1[i] = 0.f; }
;     float m = -INFINITY, lsum = 0.f, R = 1.f;
;     u32x4 rk[NKL], rv[2]; f32x4 rc = {0.f, 0.f, 0.f, 0.f};
;     const unsigned okk = (unsigned)(((tid / KCH) * DQK + (tid % KCH) * 8) * 2);
;     const unsigned ovv = (unsigned)(((tid >> 3) * ldv + (tid & 7) * 8) * 2), svv = (unsigned)(ldv * 64);
;     auto ld_tile = [&](int kt) {
;         const unsigned char* Kt = (const unsigned char*)(K + (size_t)(64 * kt) * DQK);
;         const unsigned char* Vt = (const unsigned char*)(VT + 64 * kt);
; #pragma unroll
;         for (int j = 0; j < NKL; ++j) rk[j] = *(const u32x4*)(Kt + (okk + j * 4096));
; #pragma unroll
;         for (int j = 0; j < 2; ++j) rv[j] = *(const u32x4*)(Vt + (ovv + j * svv));
;         if (cdec && tid < 16) rc = *(const f32x4*)(cdec + 64 * kt + 4 * tid);
;     };
;     auto st_tile = [&](int buf) {
;         bf16_t* sK = (bf16_t*)(smem + buf * ATT_BUF); bf16_t* sV = (bf16_t*)(smem + buf * ATT_BUF + 13312); float* sC = (float*)(smem + buf * ATT_BUF + 22528);
; #pragma unroll
;         for (int j = 0; j < NKL; ++j) { const int c = tid + 256 * j, row = c / KCH, kc = (c % KCH) * 8; *(u32x4*)(sK + row * KS + kc) = rk[j]; }
; #pragma unroll
;         for (int j = 0; j < 2; ++j) { const int c = tid + 256 * j, row = c >> 3, kc = (c & 7) * 8; *(u32x4*)(sV + row * LS + kc) = rv[j]; }
;         if (cdec && tid < 16) *(f32x4*)(sC + 4 * tid) = rc;
;     };
;     ld_tile(DESC ? ntiles - 1 : 0);
;     __syncthreads();
;     st_tile(0);
; DI void phase3(const Params& p, int l, unsigned char* smem, unsigned char* smem0) {
;     ...
;                 attn_item<64, 0, true>((const bf16_t*)(ws + O_FQ) + ((size_t)bh * S_ + q0) * 64, (const bf16_t*)(ws + O_FK) + (size_t)bh * S_ * 64,
;                                  (const bf16_t*)(ws + O_FVT) + (size_t)bh * 64 * S_, S_, (const float*)(ws + O_FC) + (size_t)bh * S_, q0, nt,
.LBB0_739:
	s_or_b64 exec, exec, s[6:7]
	v_ashrrev_i32_e32 v11, 31, v8
	v_lshrrev_b32_e32 v11, 29, v11
	v_add_u32_e32 v11, v8, v11
	v_lshrrev_b32_e32 v12, 3, v11
	v_and_b32_e32 v11, -8, v11
	s_movk_i32 s0, 0x48
	v_sub_u32_e32 v11, v8, v11
	v_mul_lo_u32 v12, v12, s0
	v_lshlrev_b32_e32 v113, 1, v12
	v_lshlrev_b32_e32 v12, 4, v11
	v_add3_u32 v12, s33, v113, v12
	v_add_u32_e32 v13, 0x100, v8
	s_waitcnt lgkmcnt(0)
	s_barrier
	s_waitcnt vmcnt(0)
	ds_write_b128 v12, v[82:85]
	v_ashrrev_i32_e32 v12, 31, v13
	v_lshrrev_b32_e32 v12, 29, v12
	v_add_u32_e32 v12, v13, v12
	v_lshrrev_b32_e32 v14, 3, v12
	v_and_b32_e32 v12, -8, v12
	v_sub_u32_e32 v12, v13, v12
	v_mul_lo_u32 v14, v14, s0
	v_lshlrev_b32_e32 v125, 1, v14
	v_lshlrev_b32_e32 v14, 4, v12
	v_add3_u32 v14, s33, v125, v14
	ds_write_b128 v14, v[86:89]
	v_lshrrev_b32_e32 v14, 3, v8
	v_lshlrev_b32_e32 v15, 3, v8
	v_lshrrev_b32_e32 v13, 3, v13
	v_and_b32_e32 v15, 56, v15
	v_mul_lo_u32 v14, v14, s0
	v_mul_lo_u32 v13, v13, s0
	v_lshlrev_b32_e32 v126, 1, v14
	v_lshlrev_b32_e32 v127, 1, v15
	v_and_b32_e32 v230, 1, v215
	v_lshlrev_b32_e32 v230, 3, v230
	v_sub_u32_e32 v230, v127, v230
	v_add_u32_e32 v230, 0x3400, v230
	v_lshlrev_b32_e32 v128, 1, v13
	v_add3_u32 v14, s33, v126, v230
	v_add3_u32 v13, s33, v128, v230
	ds_write2_b64 v14, v[90:91], v[92:93] offset1:2
	ds_write2_b64 v13, v[94:95], v[96:97] offset1:2
	s_and_saveexec_b64 s[6:7], vcc
	s_xor_b64 s[6:7], exec, s[6:7]
	v_mov_b32_e32 v111, v1
	s_andn2_saveexec_b64 s[6:7], s[6:7]
	v_ashrrev_i32_e32 v111, 31, v110
	v_lshl_add_u32 v13, v110, 2, s33
	ds_write_b128 v13, v[98:101] offset:22528
	s_or_b64 exec, exec, s[6:7]
	s_mov_b32 s0, 0xf800000
	v_mul_f32_e32 v13, 0x4f800000, v6
	v_cmp_gt_f32_e32 vcc, s0, v6
	v_lshlrev_b32_e32 v18, 3, v11
	v_lshlrev_b32_e32 v19, 3, v12
	v_cndmask_b32_e32 v6, v6, v13, vcc
	v_sqrt_f32_e32 v13, v6
	v_and_b32_e32 v8, 63, v8
	v_add_u32_e32 v130, s94, v5
	v_cmp_class_f32_e64 s[8:9], v6, v220
	v_add_u32_e32 v11, -1, v13
	v_fma_f32 v12, -v11, v13, v6
	v_cmp_ge_f32_e64 s[6:7], 0, v12
	v_add_u32_e32 v12, 1, v13
	v_mul_u32_u24_e32 v20, 0x48, v3
	v_cndmask_b32_e64 v11, v13, v11, s[6:7]
	v_fma_f32 v13, -v12, v13, v6
	v_cmp_lt_f32_e64 s[6:7], 0, v13
	v_mov_b32_e32 v16, v1
	v_mov_b32_e32 v17, v1
	v_cndmask_b32_e64 v11, v11, v12, s[6:7]
	v_cmp_gt_u32_e64 s[6:7], 32, v8
	v_mul_f32_e32 v12, 0x37800000, v11
	v_cndmask_b32_e32 v11, v11, v12, vcc
	v_cndmask_b32_e64 v9, v9, v10, s[6:7]
	v_add_f32_e32 v7, v7, v9
	v_mul_f32_e32 v9, 0x4f800000, v7
	v_cmp_gt_f32_e32 vcc, s0, v7
	v_cndmask_b32_e64 v6, v11, v6, s[8:9]
	v_mul_f32_e32 v6, 0x3f80068e, v6
	v_cndmask_b32_e32 v7, v7, v9, vcc
	v_sqrt_f32_e32 v9, v7
	v_readlane_b32 s0, v255, 6
	v_lshlrev_b32_e32 v129, 3, v4
	v_or_b32_e32 v131, v130, v3
	v_add_u32_e32 v5, -1, v9
	v_fma_f32 v10, -v5, v9, v7
	v_cmp_ge_f32_e64 s[8:9], 0, v10
	v_add_u32_e32 v10, 1, v9
	v_lshlrev_b32_e32 v112, 2, v4
	v_cndmask_b32_e64 v5, v9, v5, s[8:9]
	v_fma_f32 v9, -v10, v9, v7
	v_cmp_lt_f32_e64 s[8:9], 0, v9
	v_lshl_add_u32 v134, v2, 2, s0
	v_mov_b32_e32 v2, v1
	v_cndmask_b32_e64 v5, v5, v10, s[8:9]
	v_mul_f32_e32 v9, 0x37800000, v5
	v_cndmask_b32_e32 v5, v5, v9, vcc
	v_cmp_class_f32_e32 vcc, v7, v220
	v_cmp_eq_u32_e64 s[8:9], 0, v8
	v_mov_b32_e32 v3, v1
	v_cndmask_b32_e32 v5, v5, v7, vcc
	v_mul_f32_e32 v132, v6, v5
	v_mov_b32_e32 v4, v1
	v_mov_b32_e32 v5, v1
	v_mov_b32_e32 v6, v1
	v_mov_b32_e32 v7, v1
	v_mov_b32_e32 v8, v1
	v_mov_b32_e32 v9, v1
	v_mov_b32_e32 v10, v1
	v_mov_b32_e32 v11, v1
	v_mov_b32_e32 v12, v1
	v_mov_b32_e32 v13, v1
	v_mov_b32_e32 v14, v1
	v_mov_b32_e32 v15, v1
	v_lshlrev_b32_e32 v136, 1, v20
	v_lshlrev_b32_e32 v137, 1, v18
	v_lshlrev_b32_e32 v138, 1, v19
	v_mov_b64_e32 v[32:33], v[16:17]
	s_mov_b32 s28, 0
	v_lshl_add_u64 v[114:115], v[110:111], 2, s[12:13]
	v_or_b32_e32 v133, 31, v130
	v_sub_u32_e32 v135, 0, v129
	v_mov_b32_e32 v139, 0xff800000
	v_mov_b32_e32 v111, 0
	s_mov_b32 s14, s94
	v_mov_b64_e32 v[30:31], v[14:15]
	v_mov_b64_e32 v[28:29], v[12:13]
	v_mov_b64_e32 v[26:27], v[10:11]
	v_mov_b64_e32 v[24:25], v[8:9]
	v_mov_b64_e32 v[22:23], v[6:7]
	v_mov_b64_e32 v[20:21], v[4:5]
	v_mov_b64_e32 v[18:19], v[2:3]
	s_mov_b32 s20, 0
	s_cmp_eq_u32 s27, -1
	s_cbranch_scc1 .LBB0_759
	.p2align	6

; DI int tid_op() { int t = threadIdx.x & 255; asm volatile("" : "+v"(t)); return t; }
; DI float xhalf_other(float x, int h) { auto r = __builtin_amdgcn_permlane32_swap(__float_as_uint(x), __float_as_uint(x), false, false); return h ? __uint_as_float(r[0]) : __uint_as_float(r[1]); }
;     constexpr int KS = DQK + 8, NKS = DQK / 16, KCH = DQK / 8, NKL = 64 * KCH / 256;
;     const int tid = tid_op(), lane = tid & 63, w = tid >> 6, r = lane & 31, h = lane >> 5;
;     const int qidx = q0 + 32 * w + r;
;     bf16x8 qf[NKS];
; #pragma unroll
;     for (int s = 0; s < NKS; ++s) qf[s] = *(const bf16x8*)(Q + (size_t)(32 * w + r) * DQK + 16 * s + 8 * h);
;     float qn = 0.f;
;     if (MODE == 0 && DESC) {
; #pragma unroll
;         for (int s = 0; s < NKS; ++s)
; #pragma unroll
;             for (int j = 0; j < 8; ++j) { const float a = __uint_as_float(((unsigned)(unsigned short)qf[s][j]) << 16); qn += a * a; }
;         qn += xhalf_other(qn, h);
;         qn = sqrtf(qn) * kmax;
;     }
;     f32x16 o0, o1;
; #pragma unroll
;     for (int i = 0; i < 16; ++i) { o0[i] = 0.f; o1[i] = 0.f; }
;     float m = -INFINITY, lsum = 0.f, R = 1.f;
;     u32x4 rk[NKL], rv[2]; f32x4 rc = {0.f, 0.f, 0.f, 0.f};
;     const unsigned okk = (unsigned)(((tid / KCH) * DQK + (tid % KCH) * 8) * 2);
;     const unsigned ovv = (unsigned)(((tid >> 3) * ldv + (tid & 7) * 8) * 2), svv = (unsigned)(ldv * 64);
;     auto ld_tile = [&](int kt) {
;         const unsigned char* Kt = (const unsigned char*)(K + (size_t)(64 * kt) * DQK);
;         const unsigned char* Vt = (const unsigned char*)(VT + 64 * kt);
; #pragma unroll
;         for (int j = 0; j < NKL; ++j) rk[j] = *(const u32x4*)(Kt + (okk + j * 4096));
; #pragma unroll
;         for (int j = 0; j < 2; ++j) rv[j] = *(const u32x4*)(Vt + (ovv + j * svv));
;         if (cdec && tid < 16) rc = *(const f32x4*)(cdec + 64 * kt + 4 * tid);
;     };
.LBB0_771:
	s_and_b64 vcc, exec, s[4:5]
	s_cbranch_vccz .LBB0_786
	s_lshl_b64 s[4:5], s[10:11], 13
	s_or_b32 s4, s4, s94
	s_mulk_i32 s5, 0xc0
	s_mul_hi_u32 s6, s4, 0xc0
	s_add_i32 s5, s6, s5
	s_mulk_i32 s4, 0xc0
	v_readlane_b32 s0, v254, 58
	s_add_u32 s6, s0, s4
	v_readlane_b32 s0, v254, 59
	v_mov_b32_e32 v8, v215
	s_addc_u32 s7, s0, s5
	s_mul_i32 s4, s10, 0x180000
	v_ashrrev_i32_e32 v9, 1, v8
	v_readlane_b32 s0, v254, 60
	v_bfe_u32 v121, v8, 5, 1
	v_bfi_b32 v110, s41, v9, v8
	v_mov_b64_e32 v[2:3], s[6:7]
	s_mul_hi_u32 s5, s10, 0x180000
	s_add_u32 s4, s0, s4
	v_readlane_b32 s0, v254, 61
	v_mad_i64_i32 v[2:3], s[6:7], v110, s85, v[2:3]
	v_lshlrev_b32_e32 v0, 4, v121
	s_addc_u32 s5, s0, s5
	v_lshl_add_u64 v[2:3], v[2:3], 0, v[0:1]
	v_lshlrev_b32_e32 v0, 4, v8
	v_lshl_add_u64 v[4:5], s[4:5], 0, v[0:1]
	v_add_u32_e32 v112, 0x1000, v0
	v_mov_b32_e32 v113, v1
	v_lshl_add_u64 v[6:7], s[4:5], 0, v[112:113]
	global_load_dwordx4 v[66:69], v[4:5], off
	global_load_dwordx4 v[70:73], v[6:7], off
	v_add_u32_e32 v114, 0x2000, v0
	v_mov_b32_e32 v115, v1
	s_lshl_b64 s[6:7], s[10:11], 20
	v_lshl_add_u64 v[4:5], s[4:5], 0, v[114:115]
	v_readlane_b32 s0, v254, 62
	global_load_dwordx4 v[74:77], v[4:5], off
	s_add_u32 s6, s0, s6
	v_readlane_b32 s0, v254, 63
	s_addc_u32 s7, s0, s7
	v_lshlrev_b32_e32 v4, 11, v8
	v_and_b32_e32 v5, 0x70, v0
	s_movk_i32 s0, 0xc000
	v_and_or_b32 v116, v4, s0, v5
	v_mov_b32_e32 v117, v1
	v_lshl_add_u64 v[4:5], s[6:7], 0, v[116:117]
	global_load_dwordx4 v[78:81], v[4:5], off
	v_add_u32_e32 v118, 0x80000, v116
	v_mov_b32_e32 v119, v1
	v_lshl_add_u64 v[4:5], s[6:7], 0, v[118:119]
	global_load_dwordx4 v[82:85], v[4:5], off
	global_load_dwordx4 v[86:89], v[2:3], off
	global_load_dwordx4 v[90:93], v[2:3], off offset:32
	global_load_dwordx4 v[94:97], v[2:3], off offset:64
	global_load_dwordx4 v[98:101], v[2:3], off offset:96
	global_load_dwordx4 v[102:105], v[2:3], off offset:128
	global_load_dwordx4 v[106:109], v[2:3], off offset:160
	s_add_u32 s14, s4, 0x3000
	s_addc_u32 s15, s5, 0
	global_load_dwordx4 v[176:179], v0, s[14:15]
	global_load_dwordx4 v[180:183], v112, s[14:15]
	global_load_dwordx4 v[184:187], v114, s[14:15]
	s_mov_b32 s0, 0x2aaaaaab
	v_mul_hi_i32 v5, v8, s0
	v_add_u32_e32 v6, 0x100, v8
	v_add_u32_e32 v7, 0x200, v8
	v_lshrrev_b32_e32 v11, 31, v5
	v_ashrrev_i32_e32 v5, 1, v5
	v_mul_hi_i32 v12, v6, s0
	v_and_b32_e32 v9, 0xffffffe0, v9
	v_mul_hi_i32 v13, v7, s0
	v_add_u32_e32 v2, v5, v11
	v_lshrrev_b32_e32 v3, 31, v12
	v_ashrrev_i32_e32 v5, 1, v12
	s_movk_i32 s0, 0x68
	v_add_u32_e32 v125, s94, v9
	v_lshrrev_b32_e32 v9, 31, v13
	v_ashrrev_i32_e32 v11, 1, v13
	v_mul_lo_u32 v12, v2, 12
	v_mul_lo_u32 v2, v2, s0
	v_add_u32_e32 v3, v5, v3
	v_add_u32_e32 v5, v11, v9
	v_sub_u32_e32 v9, v8, v12
	v_lshlrev_b32_e32 v127, 1, v2
	v_mul_lo_u32 v2, v3, 12
	v_mul_lo_u32 v3, v3, s0
	v_lshlrev_b32_e32 v11, 3, v9
	v_lshlrev_b32_e32 v9, 4, v9
	v_sub_u32_e32 v2, v6, v2
	v_lshlrev_b32_e32 v128, 1, v3
	v_add3_u32 v3, s33, v127, v9
	v_lshlrev_b32_e32 v9, 3, v2
	v_lshlrev_b32_e32 v2, 4, v2
	v_add3_u32 v2, s33, v128, v2
	s_waitcnt lgkmcnt(0)
	s_barrier
; #define MFMA32(a, b, c) __builtin_amdgcn_mfma_f32_32x32x16_bf16((a), (b), (c), 0, 0, 0)
;     ...
;     f32x16 o0, o1;
; #pragma unroll
;     for (int i = 0; i < 16; ++i) { o0[i] = 0.f; o1[i] = 0.f; }
;     float m = -INFINITY, lsum = 0.f, R = 1.f;
;     u32x4 rk[NKL], rv[2]; f32x4 rc = {0.f, 0.f, 0.f, 0.f};
;     const unsigned okk = (unsigned)(((tid / KCH) * DQK + (tid % KCH) * 8) * 2);
;     const unsigned ovv = (unsigned)(((tid >> 3) * ldv + (tid & 7) * 8) * 2), svv = (unsigned)(ldv * 64);
;     auto ld_tile = [&](int kt) {
;         const unsigned char* Kt = (const unsigned char*)(K + (size_t)(64 * kt) * DQK);
;         const unsigned char* Vt = (const unsigned char*)(VT + 64 * kt);
; #pragma unroll
;         for (int j = 0; j < NKL; ++j) rk[j] = *(const u32x4*)(Kt + (okk + j * 4096));
; #pragma unroll
;         for (int j = 0; j < 2; ++j) rv[j] = *(const u32x4*)(Vt + (ovv + j * svv));
;         if (cdec && tid < 16) rc = *(const f32x4*)(cdec + 64 * kt + 4 * tid);
;     };
;     auto st_tile = [&](int buf) {
;         bf16_t* sK = (bf16_t*)(smem + buf * ATT_BUF); bf16_t* sV = (bf16_t*)(smem + buf * ATT_BUF + 13312); float* sC = (float*)(smem + buf * ATT_BUF + 22528);
; #pragma unroll
;         for (int j = 0; j < NKL; ++j) { const int c = tid + 256 * j, row = c / KCH, kc = (c % KCH) * 8; *(u32x4*)(sK + row * KS + kc) = rk[j]; }
; #pragma unroll
;         for (int j = 0; j < 2; ++j) { const int c = tid + 256 * j, row = c >> 3, kc = (c & 7) * 8; *(u32x4*)(sV + row * LS + kc) = rv[j]; }
;         if (cdec && tid < 16) *(f32x4*)(sC + 4 * tid) = rc;
;     };
;     ld_tile(DESC ? ntiles - 1 : 0);
;     __syncthreads();
;     st_tile(0);
;     ...
; #pragma unroll
;             for (int s = 0; s < NKS; ++s) {
;                 const bf16x8 k0 = *(const bf16x8*)(sK + r * KS + 16 * s + 8 * h), k1 = *(const bf16x8*)(sK + (32 + r) * KS + 16 * s + 8 * h);
;                 sc[0] = MFMA32(k0, qf[s], sc[0]);
;                 sc[1] = MFMA32(k1, qf[s], sc[1]);
;             }
	v_and_b32_e32 v4, 31, v8
	v_lshlrev_b32_e32 v10, 3, v121
	s_waitcnt vmcnt(0)
	ds_write_b128 v3, v[66:69]
	ds_write_b128 v2, v[70:73]
	v_mul_lo_u32 v2, v5, 12
	v_sub_u32_e32 v2, v7, v2
	v_mul_lo_u32 v5, v5, s0
	v_lshlrev_b32_e32 v3, 3, v2
	v_lshlrev_b32_e32 v129, 1, v5
	v_lshlrev_b32_e32 v2, 4, v2
	v_add3_u32 v2, s33, v129, v2
	ds_write_b128 v2, v[74:77]
	v_lshrrev_b32_e32 v2, 3, v8
	v_lshlrev_b32_e32 v5, 3, v8
	s_movk_i32 s0, 0x48
	v_and_b32_e32 v5, 56, v5
	v_mul_lo_u32 v2, v2, s0
	v_lshlrev_b32_e32 v130, 1, v2
	v_lshlrev_b32_e32 v131, 1, v5
	v_and_b32_e32 v217, 1, v215
	v_lshlrev_b32_e32 v217, 3, v217
	v_sub_u32_e32 v217, v131, v217
	v_add_u32_e32 v217, 0x3400, v217
	v_add3_u32 v2, s33, v130, v217
	ds_write2_b64 v2, v[78:79], v[80:81] offset1:2
	v_lshrrev_b32_e32 v2, 3, v6
	v_mul_lo_u32 v2, v2, s0
	v_lshlrev_b32_e32 v132, 1, v2
	v_add3_u32 v2, s33, v132, v217
	v_mov_b32_e32 v18, v1
	v_mov_b32_e32 v19, v1
	v_or_b32_e32 v126, v125, v4
	ds_write2_b64 v2, v[82:83], v[84:85] offset1:2
	v_mul_u32_u24_e32 v134, 0xd0, v4
	v_mul_u32_u24_e32 v136, 0x90, v4
	v_mov_b32_e32 v20, v1
	v_mov_b32_e32 v21, v1
	v_mov_b32_e32 v22, v1
	v_mov_b32_e32 v23, v1
	v_mov_b32_e32 v24, v1
	v_mov_b32_e32 v25, v1
	v_mov_b32_e32 v26, v1
	v_mov_b32_e32 v27, v1
	v_mov_b32_e32 v28, v1
	v_mov_b32_e32 v29, v1
	v_mov_b32_e32 v30, v1
	v_mov_b32_e32 v31, v1
	v_mov_b32_e32 v32, v1
	v_mov_b32_e32 v33, v1
	v_lshlrev_b32_e32 v137, 1, v10
	v_lshlrev_b32_e32 v138, 1, v11
	v_lshlrev_b32_e32 v139, 1, v9
	v_lshlrev_b32_e32 v140, 1, v3
	v_mov_b64_e32 v[2:3], v[18:19]
	s_mov_b32 s95, s49
	v_ashrrev_i32_e32 v111, 31, v110
	v_or_b32_e32 v133, 31, v125
	v_lshlrev_b32_e32 v123, 2, v121
	s_mov_b32 s16, 0
	v_mov_b32_e32 v135, 0
	v_mov_b32_e32 v122, 0xff800000
	s_mov_b32 s12, 0
	v_mov_b64_e32 v[4:5], v[20:21]
	v_mov_b64_e32 v[6:7], v[22:23]
	v_mov_b64_e32 v[8:9], v[24:25]
	v_mov_b64_e32 v[10:11], v[26:27]
	v_mov_b64_e32 v[12:13], v[28:29]
	v_mov_b64_e32 v[14:15], v[30:31]
	v_mov_b64_e32 v[16:17], v[32:33]
	v_mov_b32_e32 v156, 0
	v_mov_b32_e32 v157, 0
	v_mov_b32_e32 v158, 0
	v_mov_b32_e32 v159, 0
	v_mov_b32_e32 v160, 0
	v_mov_b32_e32 v161, 0
	v_mov_b32_e32 v162, 0
	v_mov_b32_e32 v163, 0
	v_mov_b32_e32 v164, 0
	v_mov_b32_e32 v165, 0
	v_mov_b32_e32 v166, 0
	v_mov_b32_e32 v167, 0
	v_mov_b32_e32 v168, 0
	v_mov_b32_e32 v169, 0
	v_mov_b32_e32 v170, 0
	v_mov_b32_e32 v171, 0
	s_mov_b64 s[20:21], -1
	v_add3_u32 v127, s33, v127, v138
	v_add3_u32 v128, s33, v128, v139
	v_add3_u32 v129, s33, v129, v140
	v_add3_u32 v130, s33, v130, v217
	v_add3_u32 v132, s33, v132, v217
	v_add_u32_e32 v138, 0x5900, v130
	v_add_u32_e32 v139, 0x5900, v132
	v_add3_u32 v216, s33, v134, v137
	v_lshlrev_b32_e32 v231, 2, v123
	v_add3_u32 v231, s33, v136, v231
	s_lshr_b32 s31, s72, 1
	s_add_i32 s31, s31, 0x122c0
	v_mov_b32_e32 v155, s31
	v_mov_b32_e32 v172, 1
	v_mov_b32_e32 v173, 0
	ds_write_b32 v155, v173
	s_mov_b32 s30, 0
	ds_write_b128 v127, v[176:179] offset:22784
	ds_write_b128 v128, v[180:183] offset:22784
	ds_write_b128 v129, v[184:187] offset:22784
	s_waitcnt lgkmcnt(0)
	s_barrier
	ds_read_b128 v[208:211], v216 offset:0
	ds_read_b128 v[232:235], v216 offset:6656
	ds_read_b128 v[236:239], v216 offset:32
	ds_read_b128 v[240:243], v216 offset:6688
	ds_read_b128 v[244:247], v216 offset:64
	ds_read_b128 v[248:251], v216 offset:6720
	s_waitcnt lgkmcnt(4)
	v_mfma_f32_32x32x16_bf16 v[50:65], v[208:211], v[86:89], 0
	v_mfma_f32_32x32x16_bf16 v[34:49], v[232:235], v[86:89], 0
	ds_read_b128 v[208:211], v216 offset:96
	ds_read_b128 v[232:235], v216 offset:6752
	s_waitcnt lgkmcnt(4)
	v_mfma_f32_32x32x16_bf16 v[50:65], v[236:239], v[90:93], v[50:65]
	v_mfma_f32_32x32x16_bf16 v[34:49], v[240:243], v[90:93], v[34:49]
	ds_read_b128 v[236:239], v216 offset:128
	ds_read_b128 v[240:243], v216 offset:6784
	s_waitcnt lgkmcnt(4)
	v_mfma_f32_32x32x16_bf16 v[50:65], v[244:247], v[94:97], v[50:65]
	v_mfma_f32_32x32x16_bf16 v[34:49], v[248:251], v[94:97], v[34:49]
	ds_read_b128 v[244:247], v216 offset:160
	ds_read_b128 v[248:251], v216 offset:6816
	s_waitcnt lgkmcnt(4)
	v_mfma_f32_32x32x16_bf16 v[50:65], v[208:211], v[98:101], v[50:65]
	v_mfma_f32_32x32x16_bf16 v[34:49], v[232:235], v[98:101], v[34:49]
	s_waitcnt lgkmcnt(2)
	v_mfma_f32_32x32x16_bf16 v[50:65], v[236:239], v[102:105], v[50:65]
	v_mfma_f32_32x32x16_bf16 v[34:49], v[240:243], v[102:105], v[34:49]
	s_waitcnt lgkmcnt(0)
	v_mfma_f32_32x32x16_bf16 v[50:65], v[244:247], v[106:109], v[50:65]
	v_mfma_f32_32x32x16_bf16 v[34:49], v[248:251], v[106:109], v[34:49]
	s_nop 7
	s_nop 3
	.p2align	6

; DI int tid8_op() { int t = threadIdx.x; asm volatile("" : "+v"(t)); return t; }
; DI void phase4(const Params& p, int l, unsigned char* smem) {
;     unsigned char* ws = p.ws; asm volatile("" : "+s"(ws));
;     const int tid = tid8_op(), lane = tid & 63, w = __builtin_amdgcn_readfirstlane(tid >> 6), wr = w >> 2, wc = w & 3, r = lane & 31, h = lane >> 5;
;     const bf16_t* YB = (const bf16_t*)(ws + O_YB); const bf16_t* MR = (const bf16_t*)(ws + O_MR);
;     const bf16_t* WMU = (const bf16_t*)(ws + O_WMU + l * SZ_WMU); const bf16_t* WBR = (const bf16_t*)(ws + O_WBR + l * SZ_WBR);
;     const int G = gridDim.x, ntl = 2048, vb = blockIdx.x;
;     if (vb >= ntl) return;
;     const int nmine = (ntl - vb + G - 1) / G, gmax = nmine * 24 - 1;
;     bf16_t* sA = (bf16_t*)smem; bf16_t* sB = sA + 2 * TILE_E;
;     const int srow = tid >> 3, skc = (tid & 7) * 8;
;     const unsigned o128 = (unsigned)((srow * 128 + skc) * 2), s128 = 128u * 128u, o1024 = (unsigned)((srow * 1024 + skc) * 2), s1024 = 1024u * 128u;
;     auto ISS = [&](Stg4& R, int g) {
;         g = g < gmax ? g : gmax;
;         const int i = g / 24, v = g - i * 24, n = v / 6, jj = v - n * 6;
;         const int t = vb + i * G, xcd = t & 7, j = t >> 3, m0 = (32 * xcd + (j >> 3)) * 128, c0 = (j & 7) * 128;
;         if (jj < 2) stg4_issue(R, MR + (size_t)m0 * 128 + jj * 64, o128, s128, WMU + (size_t)(n * 1024 + c0) * 128 + jj * 64, o128, s128);
;         else stg4_issue(R, YB + (size_t)m0 * 1024 + n * 256 + (jj - 2) * 64, o1024, s1024, WBR + (size_t)c0 * 1024 + n * 256 + (jj - 2) * 64, o1024, s1024);
;     };
;     Stg4 R0, R1;
;     ISS(R0, 0); ISS(R1, 1);
;     stg4_commit(R0, sA, sB, srow, skc);
;     ISS(R0, 2);
.LBB0_850:
	s_or_b64 exec, exec, s[36:37]
	v_readlane_b32 s0, v253, 40
	s_mov_b64 s[4:5], s[76:77]
	v_mov_b32_e32 v22, v214
	v_readlane_b32 s1, v253, 41
	s_waitcnt lgkmcnt(0)
	s_barrier
	s_and_b64 vcc, exec, s[0:1]
	v_readfirstlane_b32 s12, v22
	s_cbranch_vccz .LBB0_892
	s_add_u32 s6, s4, 0x1a4c3900
	s_addc_u32 s7, s5, 0
	s_add_u32 s8, s4, 0x15080000
	s_addc_u32 s9, s5, 0
	v_readlane_b32 s0, v254, 56
	v_readlane_b32 s1, v254, 57
	s_add_u32 s10, s4, s0
	s_addc_u32 s11, s5, s1
	s_add_u32 s10, s10, 0x2480000
	s_addc_u32 s11, s11, 0
	s_lshl_b64 s[12:13], s[40:41], 21
	s_add_u32 s12, s4, s12
	s_addc_u32 s13, s5, s13
	s_add_u32 s12, s12, 0x2880000
	s_addc_u32 s13, s13, 0
	s_add_u32 s14, s4, 0x3880000
	s_addc_u32 s15, s5, 0
	v_and_b32_e32 v0, 31, v214
	v_bfe_u32 v2, v214, 5, 1
	v_readfirstlane_b32 s0, v214
	s_lshr_b32 s0, s0, 6
	s_lshr_b32 s1, s0, 2
	s_and_b32 s0, s0, 3
	v_lshlrev_b32_e32 v186, 4, v214
	v_add_u32_e32 v187, 0x2000, v186
	v_add_u32_e32 v188, 0x4000, v186
	v_add_u32_e32 v189, 0x6000, v186
	v_lshrrev_b32_e32 v3, 4, v214
	v_and_b32_e32 v4, 15, v214
	v_lshlrev_b32_e32 v5, 4, v4
	v_lshl_add_u32 v190, v3, 11, v5
	v_add_u32_e32 v191, 0x10000, v190
	v_add_u32_e32 v192, 0x20000, v190
	v_add_u32_e32 v193, 0x30000, v190
	v_mul_u32_u24_e32 v194, 0x110, v3
	v_add_u32_e32 v194, v194, v5
	v_add_u32_e32 v195, 0x11000, v194
	s_lshl_b32 s16, s1, 6
	v_add_u32_e32 v3, s16, v0
	v_mul_u32_u24_e32 v3, 0x110, v3
	v_lshl_add_u32 v196, v2, 4, v3
	v_add_u32_e32 v197, 0x11000, v196
	s_lshl_b32 s16, s0, 5
	v_add_u32_e32 v3, s16, v0
	v_mul_u32_u24_e32 v3, 0x110, v3
	v_lshl_add_u32 v3, v2, 4, v3
	v_add_u32_e32 v198, 0x8800, v3
	v_add_u32_e32 v199, 0x11000, v198
	v_lshlrev_b32_e32 v3, 2, v2
	s_lshl_b32 s16, s1, 6
	v_add_u32_e32 v3, s16, v3
	v_lshlrev_b32_e32 v3, 11, v3
	s_lshl_b32 s16, s0, 5
	v_add_u32_e32 v4, s16, v0
	v_lshl_add_u32 v200, v4, 1, v3
	v_mov_b32_e32 v66, 0
	v_mov_b32_e32 v67, 0
	v_mov_b32_e32 v68, 0
	v_mov_b32_e32 v69, 0
	v_mov_b32_e32 v70, 0
	v_mov_b32_e32 v71, 0
	v_mov_b32_e32 v72, 0
	v_mov_b32_e32 v73, 0
	v_mov_b32_e32 v74, 0
	v_mov_b32_e32 v75, 0
	v_mov_b32_e32 v76, 0
	v_mov_b32_e32 v77, 0
	v_mov_b32_e32 v78, 0
	v_mov_b32_e32 v79, 0
	v_mov_b32_e32 v80, 0
	v_mov_b32_e32 v81, 0
	v_mov_b32_e32 v82, 0
	v_mov_b32_e32 v83, 0
	v_mov_b32_e32 v84, 0
	v_mov_b32_e32 v85, 0
	v_mov_b32_e32 v86, 0
	v_mov_b32_e32 v87, 0
	v_mov_b32_e32 v88, 0
	v_mov_b32_e32 v89, 0
	v_mov_b32_e32 v90, 0
	v_mov_b32_e32 v91, 0
	v_mov_b32_e32 v92, 0
	v_mov_b32_e32 v93, 0
	v_mov_b32_e32 v94, 0
	v_mov_b32_e32 v95, 0
	v_mov_b32_e32 v96, 0
	v_mov_b32_e32 v97, 0
	s_mov_b32 s25, s2
	s_mov_b32 s24, 0
	s_and_b32 s20, s25, 7
	s_lshl_b32 s20, s20, 5
	s_lshr_b32 s21, s25, 6
	s_add_i32 s20, s20, s21
	s_lshl_b32 s26, s20, 7
	s_bfe_u32 s20, s25, 0x30003
	s_lshl_b32 s27, s20, 7
	s_mov_b32 s28, 0
	s_lshl_b32 s20, s26, 8
	s_add_u32 s16, s8, s20
	s_addc_u32 s17, s9, 0
	s_lshl_b32 s20, s28, 10
	s_add_i32 s20, s20, s27
	s_lshl_b32 s20, s20, 8
	s_add_u32 s18, s10, s20
	s_addc_u32 s19, s11, 0
	global_load_dwordx4 v[98:101], v186, s[16:17]
	global_load_dwordx4 v[102:105], v187, s[16:17]
	global_load_dwordx4 v[106:109], v188, s[16:17]
	global_load_dwordx4 v[110:113], v189, s[16:17]
	global_load_dwordx4 v[114:117], v186, s[18:19]
	global_load_dwordx4 v[118:121], v187, s[18:19]
	global_load_dwordx4 v[122:125], v188, s[18:19]
	global_load_dwordx4 v[126:129], v189, s[18:19]
	s_lshl_b32 s20, s26, 11
	s_lshl_b32 s21, s28, 9
	s_add_i32 s21, s21, 0
	s_add_i32 s20, s20, s21
	s_add_u32 s16, s6, s20
	s_addc_u32 s17, s7, 0
	s_lshl_b32 s20, s27, 11
	s_add_i32 s20, s20, s21
	s_add_u32 s18, s12, s20
	s_addc_u32 s19, s13, 0
	global_load_dwordx4 v[130:133], v190, s[16:17]
	global_load_dwordx4 v[134:137], v191, s[16:17]
	global_load_dwordx4 v[138:141], v192, s[16:17]
	global_load_dwordx4 v[142:145], v193, s[16:17]
	global_load_dwordx4 v[146:149], v190, s[18:19]
	global_load_dwordx4 v[150:153], v191, s[18:19]
	global_load_dwordx4 v[154:157], v192, s[18:19]
	global_load_dwordx4 v[158:161], v193, s[18:19]
	s_waitcnt vmcnt(8)
	ds_write_b128 v194, v[98:101] offset:0
	ds_write_b128 v194, v[102:105] offset:8704
	ds_write_b128 v194, v[106:109] offset:17408
	ds_write_b128 v194, v[110:113] offset:26112
	ds_write_b128 v194, v[114:117] offset:34816
	ds_write_b128 v194, v[118:121] offset:43520
	ds_write_b128 v194, v[122:125] offset:52224
	ds_write_b128 v194, v[126:129] offset:60928
	.p2align	6
